# grid barrier (2nd use onward): all workgroups poll the cross-XCD arrival counter directly; no generation words
# baseline (speedup 1.0000x reference)
.LBB0_37:
	v_readlane_b32 s20, v210, 43
	v_readlane_b32 s21, v210, 44
	v_cmp_ne_u32_e32 vcc, 0, v16
	s_nop 0
	v_cndmask_b32_e64 v17, 0, v16, s[20:21]
	v_readlane_b32 s20, v210, 41
	v_readlane_b32 s21, v210, 42
	v_cndmask_b32_e64 v16, 0, 1, vcc
	v_cmp_ne_u32_e32 vcc, 0, v0
	v_cndmask_b32_e64 v17, v17, v0, s[20:21]
	v_readlane_b32 s20, v210, 39
	v_readlane_b32 s21, v210, 40
	v_addc_co_u32_e32 v0, vcc, 0, v16, vcc
	s_nop 0
	v_cndmask_b32_e64 v17, v17, v2, s[20:21]
	v_readlane_b32 s20, v210, 37
	v_readlane_b32 s21, v210, 38
	v_cmp_ne_u32_e32 vcc, 0, v2
	s_nop 0
	v_cndmask_b32_e64 v17, v17, v3, s[20:21]
	v_readlane_b32 s20, v210, 35
	v_readlane_b32 s21, v210, 36
	v_cndmask_b32_e64 v2, 0, 1, vcc
	v_cmp_ne_u32_e32 vcc, 0, v3
	v_cndmask_b32_e64 v17, v17, v4, s[20:21]
	v_readlane_b32 s20, v210, 33
	v_readlane_b32 s21, v210, 34
	v_addc_co_u32_e32 v0, vcc, v0, v2, vcc
	s_nop 0
	v_cndmask_b32_e64 v17, v17, v5, s[20:21]
	v_readlane_b32 s20, v210, 31
	v_readlane_b32 s21, v210, 32
	v_cmp_ne_u32_e32 vcc, 0, v4
	s_nop 0
	v_cndmask_b32_e64 v17, v17, v6, s[20:21]
	v_readlane_b32 s20, v210, 29
	v_readlane_b32 s21, v210, 30
	v_cndmask_b32_e64 v2, 0, 1, vcc
	v_cmp_ne_u32_e32 vcc, 0, v5
	v_cndmask_b32_e64 v17, v17, v7, s[20:21]
	v_readlane_b32 s20, v210, 27
	v_readlane_b32 s21, v210, 28
	v_addc_co_u32_e32 v0, vcc, v0, v2, vcc
	s_nop 0
	v_cndmask_b32_e64 v17, v17, v8, s[20:21]
	v_readlane_b32 s20, v210, 25
	v_cmp_ne_u32_e32 vcc, 0, v6
	v_readlane_b32 s21, v210, 26
	s_nop 0
	v_cndmask_b32_e64 v2, 0, 1, vcc
	v_cmp_ne_u32_e32 vcc, 0, v7
	v_cndmask_b32_e64 v17, v17, v9, s[20:21]
	v_readlane_b32 s20, v210, 23
	v_addc_co_u32_e32 v0, vcc, v0, v2, vcc
	v_readlane_b32 s21, v210, 24
	v_cmp_ne_u32_e32 vcc, 0, v8
	s_nop 0
	v_cndmask_b32_e64 v17, v17, v10, s[20:21]
	v_readlane_b32 s20, v210, 21
	v_cndmask_b32_e64 v2, 0, 1, vcc
	v_cmp_ne_u32_e32 vcc, 0, v9
	v_readlane_b32 s21, v210, 22
	s_nop 0
	v_addc_co_u32_e32 v0, vcc, v0, v2, vcc
	v_cndmask_b32_e64 v17, v17, v11, s[20:21]
	v_readlane_b32 s20, v210, 19
	v_cmp_ne_u32_e32 vcc, 0, v10
	v_readlane_b32 s21, v210, 20
	s_nop 0
	v_cndmask_b32_e64 v2, 0, 1, vcc
	v_cmp_ne_u32_e32 vcc, 0, v11
	v_cndmask_b32_e64 v17, v17, v12, s[20:21]
	v_readlane_b32 s20, v210, 17
	v_addc_co_u32_e32 v0, vcc, v0, v2, vcc
	v_readlane_b32 s21, v210, 18
	v_cmp_ne_u32_e32 vcc, 0, v12
	s_nop 0
	v_cndmask_b32_e64 v17, v17, v13, s[20:21]
	v_readlane_b32 s20, v210, 15
	v_cndmask_b32_e64 v2, 0, 1, vcc
	v_cmp_ne_u32_e32 vcc, 0, v13
	v_readlane_b32 s21, v210, 16
	s_nop 0
	v_addc_co_u32_e32 v0, vcc, v0, v2, vcc
	v_cndmask_b32_e64 v17, v17, v14, s[20:21]
	v_readlane_b32 s20, v210, 13
	v_cmp_ne_u32_e32 vcc, 0, v14
	v_readlane_b32 s21, v210, 14
	s_nop 0
	v_cndmask_b32_e64 v2, 0, 1, vcc
	v_cmp_ne_u32_e32 vcc, 0, v15
	v_cndmask_b32_e64 v17, v17, v15, s[20:21]
	v_max_u32_e32 v3, 1, v17
	v_addc_co_u32_e32 v0, vcc, v0, v2, vcc
	v_max_u32_e32 v0, 1, v0
	ds_write_b32 v1, v3
	ds_write_b32 v1, v0 offset:4
	s_branch .LBB0_38
.Lxb_fast:
	s_waitcnt lgkmcnt(0)
	v_readfirstlane_b32 s42, v3
	v_readfirstlane_b32 s43, v0
	v_readlane_b32 s44, v209, 42
	v_readlane_b32 s8, v209, 12
	s_nop 3
	s_mul_i32 s45, s44, s42
	s_mul_i32 s46, s44, s43
	s_add_u32 s48, s40, s8
	s_addc_u32 s49, s41, 0
	v_mov_b32_e32 v4, 1
	global_atomic_add v4, v156, v4, s[48:49] offset:1024 sc0
	s_waitcnt vmcnt(0)
	v_readfirstlane_b32 s47, v4
	s_nop 3
	s_add_i32 s47, s47, 1
	s_cmp_lg_u32 s47, s45
	s_cbranch_scc1 .Lxb_wait
	buffer_wbl2 sc1
	s_waitcnt vmcnt(0)
	v_mov_b32_e32 v4, 1
	global_atomic_add v158, v4, s[40:41] offset:1024
.Lxb_wait:
	s_mov_b32 s45, 0x1000
.Lxb_spin:
	global_load_dword v4, v158, s[40:41] offset:1024 sc1
	s_waitcnt vmcnt(0)
	v_readfirstlane_b32 s42, v4
	s_nop 3
	s_cmp_ge_u32 s42, s46
	s_cbranch_scc1 .Lxb_done
	s_sleep 1
	s_sub_i32 s45, s45, 1
	s_cmp_lg_u32 s45, 0
	s_cbranch_scc1 .Lxb_spin
	v_mov_b32_e32 v4, 1
	global_atomic_add v1, v4, s[40:41] offset:512
.Lxb_done:
	s_waitcnt vmcnt(0)
	buffer_inv sc1
	s_waitcnt vmcnt(0)
	s_branch .LBB0_74
